# phase 4/7 row reductions: ds_bpermute butterflies replaced by DPP quad_perm/row_mirror adds and permlane16/32 swaps (no LDS round trips)
# speedup vs baseline: 1.0029x; 1.0029x over previous
; __device__ __forceinline__ float bflo(unsigned w) { return __uint_as_float(w << 16); }
; __device__ __forceinline__ float bfhi(unsigned w) { return __uint_as_float(w & 0xffff0000u); }
; __device__ __forceinline__ float sigm(float x) { return __builtin_amdgcn_rcpf(1.f + __expf(-x)); }
; #define OB_LOAD(it) do { const size_t r_ = (size_t)r0 + (it) * 8 + wid; const bf16_t* pr_ = P0 + r_ * LDP; \
;         pre[0] = *(const u32x4*)(pr_ + col); pre[1] = *(const u32x4*)(pr_ + 512 + col); pre[2] = *(const u32x4*)(pr_ + 2048 + col); pre[3] = *(const u32x4*)(pr_ + 2560 + col); \
;         pre[4] = *(const u32x4*)(CAT0 + r_ * 1024 + 512 + col); } while (0)
; __device__ void panel_outb(const Params& p, int r0) {
;     ...
;     for (int it = 0; it < 32; ++it) {
;         const size_t r = (size_t)r0 + it * 8 + wid;
;         const u32x4 hf = pre[0], hb = pre[1], ob = pre[2], zb = pre[3], xc = pre[4];
;         OB_LOAD((it + 1 < 32) ? it + 1 : it);
;         float hv[8], o[8], z[8], x[8];
; #pragma unroll
;         for (int w = 0; w < 4; ++w) { hv[2 * w] = bflo(hf[w]) + bflo(hb[w]); hv[2 * w + 1] = bfhi(hf[w]) + bfhi(hb[w]); o[2 * w] = bflo(ob[w]); o[2 * w + 1] = bfhi(ob[w]);
;             z[2 * w] = bflo(zb[w]); z[2 * w + 1] = bfhi(zb[w]); x[2 * w] = bflo(xc[w]); x[2 * w + 1] = bfhi(xc[w]); }
;         float s = 0.f;
; #pragma unroll
;         for (int e = 0; e < 8; ++e) { hv[e] *= sigm(o[e]); s += hv[e]; }
;         s += __shfl_xor(s, 1); s += __shfl_xor(s, 2); s += __shfl_xor(s, 4); s += __shfl_xor(s, 8);
;         const float mu = s * (1.f / 128.f); float v = 0.f;
; #pragma unroll
;         for (int e = 0; e < 8; ++e) { hv[e] -= mu; v += hv[e] * hv[e]; }
;         v += __shfl_xor(v, 1); v += __shfl_xor(v, 2); v += __shfl_xor(v, 4); v += __shfl_xor(v, 8);
;         const float rstd = rsqrtf(v * (1.f / 128.f) + 1e-5f);
.LBB0_372:
	v_lshlrev_b32_e32 v4, 16, v28
	v_lshlrev_b32_e32 v6, 16, v32
	v_add_f32_e32 v6, v6, v4
	v_and_b32_e32 v4, 0xffff0000, v32
	v_and_b32_e32 v12, 0xffff0000, v28
	v_add_f32_e32 v12, v4, v12
	v_lshlrev_b32_e32 v4, 16, v24
	v_and_b32_e32 v14, 0xffff0000, v24
	v_mul_f32_e32 v4, 0xbfb8aa3b, v4
	v_exp_f32_e32 v4, v4
	v_mul_f32_e32 v14, 0xbfb8aa3b, v14
	v_exp_f32_e32 v14, v14
	v_lshlrev_b32_e32 v40, 16, v25
	v_add_f32_e32 v4, 1.0, v4
	v_rcp_f32_e32 v44, v4
	v_add_f32_e32 v4, 1.0, v14
	v_and_b32_e32 v42, 0xffff0000, v25
	v_rcp_f32_e32 v14, v4
	v_mul_f32_e32 v4, 0xbfb8aa3b, v40
	v_lshlrev_b32_e32 v53, 16, v29
	v_and_b32_e32 v52, 0xffff0000, v29
	v_lshlrev_b32_e32 v25, 16, v34
	v_lshlrev_b32_e32 v29, 16, v30
	v_and_b32_e32 v24, 0xffff0000, v34
	v_and_b32_e32 v28, 0xffff0000, v30
	v_lshlrev_b32_e32 v30, 16, v26
	v_and_b32_e32 v34, 0xffff0000, v26
	v_exp_f32_e32 v4, v4
	v_mul_f32_e32 v26, 0xbfb8aa3b, v42
	v_lshlrev_b32_e32 v51, 16, v33
	v_and_b32_e32 v50, 0xffff0000, v33
	v_lshlrev_b32_e32 v33, 16, v35
	v_and_b32_e32 v32, 0xffff0000, v35
	v_lshlrev_b32_e32 v35, 16, v27
	v_and_b32_e32 v40, 0xffff0000, v27
	v_exp_f32_e32 v26, v26
	v_mul_f32_e32 v27, 0xbfb8aa3b, v30
	v_exp_f32_e32 v30, v27
	v_add_f32_e32 v4, 1.0, v4
	v_rcp_f32_e32 v27, v4
	v_add_f32_e32 v4, 1.0, v26
	v_rcp_f32_e32 v26, v4
	v_add_f32_e32 v4, 1.0, v30
	v_mul_f32_e32 v30, 0xbfb8aa3b, v35
	v_lshlrev_b32_e32 v55, 16, v31
	v_and_b32_e32 v54, 0xffff0000, v31
	v_rcp_f32_e32 v31, v4
	v_mul_f32_e32 v4, 0xbfb8aa3b, v34
	v_exp_f32_e32 v30, v30
	v_mul_f32_e32 v34, 0xbfb8aa3b, v40
	v_exp_f32_e32 v34, v34
	v_exp_f32_e32 v4, v4
	v_add_f32_e32 v30, 1.0, v30
	v_rcp_f32_e32 v35, v30
	v_add_f32_e32 v30, 1.0, v34
	v_add_f32_e32 v4, 1.0, v4
	v_rcp_f32_e32 v34, v30
	v_rcp_f32_e32 v30, v4
	v_fma_f32 v46, v6, v44, 0
	v_pk_add_f32 v[50:51], v[52:53], v[50:51]
	v_fmac_f32_e32 v46, v12, v14
	v_pk_mul_f32 v[52:53], v[50:51], v[26:27]
	v_pk_add_f32 v[24:25], v[28:29], v[24:25]
	v_add_f32_e32 v4, v53, v46
	v_pk_mul_f32 v[28:29], v[24:25], v[30:31]
	v_add_f32_e32 v4, v52, v4
	v_pk_add_f32 v[32:33], v[54:55], v[32:33]
	v_add_f32_e32 v4, v29, v4
	v_pk_mul_f32 v[54:55], v[32:33], v[34:35]
	v_add_f32_e32 v4, v28, v4
	v_add_f32_e32 v4, v55, v4
	v_add_f32_e32 v4, v54, v4
	s_cmpk_lg_i32 s11, 0x100
	s_cselect_b32 s0, s11, 0xf8
	v_lshl_add_u64 v[54:55], v[142:143], 0, s[0:1]
	v_lshlrev_b32_e32 v128, 1, v132
	s_nop 1
	v_add_f32_dpp v4, v4, v4 quad_perm:[1,0,3,2] row_mask:0xf bank_mask:0xf
	v_lshlrev_b32_e32 v64, 16, v20
	v_and_b32_e32 v66, 0xffff0000, v20
	v_lshlrev_b32_e32 v65, 16, v16
	v_and_b32_e32 v67, 0xffff0000, v16
	s_nop 1
	v_add_f32_dpp v4, v4, v4 quad_perm:[2,3,0,1] row_mask:0xf bank_mask:0xf
	v_lshlrev_b32_e32 v20, 16, v21
	v_and_b32_e32 v16, 0xffff0000, v21
	v_lshlrev_b32_e32 v21, 16, v17
	v_and_b32_e32 v17, 0xffff0000, v17
	s_nop 1
	v_add_f32_dpp v4, v4, v4 row_half_mirror row_mask:0xf bank_mask:0xf
	v_mov_b64_e32 v[28:29], s[78:79]
	v_mad_u64_u32 v[28:29], s[14:15], v54, s3, v[28:29]
	s_add_i32 s11, s11, 8
	s_nop 1
	v_add_f32_dpp v4, v4, v4 row_mirror row_mask:0xf bank_mask:0xf
	v_mul_f32_e32 v4, 0x3c000000, v4
	v_fma_f32 v12, v12, v14, -v4
	v_fma_f32 v6, v6, v44, -v4
	v_mul_f32_e32 v14, v12, v12
	v_pk_fma_f32 v[58:59], v[50:51], v[26:27], v[4:5] op_sel_hi:[1,1,0] neg_lo:[0,0,1] neg_hi:[0,0,1]
	v_fmac_f32_e32 v14, v6, v6
	v_pk_mul_f32 v[26:27], v[58:59], v[58:59]
	v_pk_fma_f32 v[60:61], v[24:25], v[30:31], v[4:5] op_sel_hi:[1,1,0] neg_lo:[0,0,1] neg_hi:[0,0,1]
	v_add_f32_e32 v14, v27, v14
	v_add_f32_e32 v14, v26, v14
	v_pk_mul_f32 v[24:25], v[60:61], v[60:61]
	v_pk_fma_f32 v[62:63], v[32:33], v[34:35], v[4:5] op_sel_hi:[1,1,0] neg_lo:[0,0,1] neg_hi:[0,0,1]
	v_add_f32_e32 v14, v25, v14
	v_add_f32_e32 v14, v24, v14
	v_pk_mul_f32 v[24:25], v[62:63], v[62:63]
	s_cmpk_lg_i32 s11, 0x108
	v_add_f32_e32 v4, v25, v14
	v_add_f32_e32 v14, v24, v4
	v_mov_b32_e32 v4, v29
	v_mad_u64_u32 v[24:25], s[14:15], v55, s3, v[4:5]
	v_mov_b32_e32 v29, v24
	s_nop 1
	v_add_f32_dpp v4, v14, v14 quad_perm:[1,0,3,2] row_mask:0xf bank_mask:0xf
	v_lshl_add_u64 v[24:25], v[28:29], 0, v[128:129]
	v_add_co_u32_e32 v56, vcc, s10, v24
	v_lshlrev_b64 v[54:55], 11, v[54:55]
	s_nop 1
	v_add_f32_dpp v4, v4, v4 quad_perm:[2,3,0,1] row_mask:0xf bank_mask:0xf
	v_addc_co_u32_e32 v57, vcc, 0, v25, vcc
	v_lshl_add_u64 v[54:55], v[36:37], 0, v[54:55]
	global_load_dwordx4 v[32:35], v[24:25], off
	global_load_dwordx4 v[28:31], v[24:25], off offset:1024
	s_nop 0
	global_load_dwordx4 v[24:27], v[56:57], off
	global_load_dwordx4 v[50:53], v[56:57], off offset:1024
	s_nop 1
	v_add_f32_dpp v4, v4, v4 row_half_mirror row_mask:0xf bank_mask:0xf
	global_load_dwordx4 v[54:57], v[54:55], off offset:1024
	s_nop 1
	v_add_f32_dpp v4, v4, v4 row_mirror row_mask:0xf bank_mask:0xf
	v_fmamk_f32 v4, v4, 0x3c000000, v48
	v_mul_f32_e32 v14, 0x4b800000, v4
	v_cmp_gt_f32_e32 vcc, s12, v4
	s_nop 1
	v_cndmask_b32_e32 v4, v4, v14, vcc
	v_rsq_f32_e32 v4, v4
	v_mul_f32_e32 v14, 0xbfb8aa3b, v64
	v_exp_f32_e32 v14, v14
	v_mul_f32_e32 v40, 0x45800000, v4
	v_cndmask_b32_e32 v49, v4, v40, vcc
	v_mul_f32_e32 v4, v6, v49
	v_add_f32_e32 v6, 1.0, v14
	v_rcp_f32_e32 v40, v6
	v_mul_f32_e32 v6, 0xbfb8aa3b, v66
	v_exp_f32_e32 v6, v6
	v_pk_mul_f32 v[64:65], v[40:41], v[64:65]
	s_nop 0
	v_fma_f32 v14, v0, v4, v65
	v_add_f32_e32 v4, 1.0, v6
	v_rcp_f32_e32 v4, v4
	v_mul_f32_e32 v40, v64, v14
	v_mul_f32_e32 v6, v12, v49
	v_pk_mul_f32 v[64:65], v[4:5], v[66:67]
	v_mul_f32_e32 v4, 0xbfb8aa3b, v20
	v_exp_f32_e32 v4, v4
	v_fma_f32 v6, v1, v6, v65
	v_mul_f32_e32 v64, v64, v6
; __device__ __forceinline__ unsigned cvt_pk(float lo, float hi) { unsigned r; asm volatile("v_cvt_pk_bf16_f32 %0, %1, %2" : "=v"(r) : "v"(lo), "v"(hi)); return r; }
; __device__ __forceinline__ float silu(float x) { return x * sigm(x); }
; #define PG8_WAIT_V(n) asm volatile("s_waitcnt vmcnt(" #n ")" ::: "memory")
; template <class Epi, class Sched>
; __device__ __forceinline__ void gemm_phase(LAS unsigned char* lds, const Gemm g, const Sched& S, const Epi& E) {
;     ...
;     for (int i = 0; i < 2; ++i) { int R, C; stage_rc(tid * 16 + i * 8192, R, C); const int Rb = Epi::PERM ? ((R & ~31) + perm32(R & 31)) : R;
;         voffA[i] = (unsigned)(R * lda + C) * 2u; voffB[i] = (unsigned)(Rb * K + C) * 2u; }
;     const size_t kstep = (size_t)(BK * 2);
;     const size_t hA = (size_t)HALF * lda * 2, hB = (size_t)HALF * K * 2;
;     const size_t tA = 2 * hA, tB = 2 * hB;
;     const unsigned ldsw = (unsigned)wid * 1024u;
;     const int aoff = lds_byte(wr * 64 + fr, fq * 8), boff = lds_byte(wc * 32 + fr, fq * 8);
;     ...
;     Unit cur, nxt; int ui = 0;
;     if (!S.next(0, cur)) return;
;     f32x4 acc[2][2][4][2];
; #pragma unroll
;     for (int a = 0; a < 2; ++a)
; #pragma unroll
;         for (int b = 0; b < 2; ++b)
; #pragma unroll
;             for (int m = 0; m < 4; ++m)
; #pragma unroll
;                 for (int n = 0; n < 2; ++n) acc[a][b][m][n] = (f32x4){0.f, 0.f, 0.f, 0.f};
;     bf16x8 At[4][2], B0[2][2], B1[2][2];
;     const char* cA = (const char*)g.A + (size_t)cur.pm * tA; const char* cB = (const char*)g.Bt + (size_t)cur.pn * tB;
;     PG8_STAGE(PG8_SB(0, 0), cB, voffB); PG8_STAGE(PG8_SA(0, 0), cA, voffA); PG8_STAGE(PG8_SB(0, 1), cB + hB, voffB); PG8_STAGE(PG8_SA(0, 1), cA + hA, voffA);
;     if (wr == 1) PG8_BAR;
;     PG8_WAIT_V(4); PG8_BAR;
;     PG8_STAGE(PG8_SB(1, 0), cB + kstep, voffB); PG8_STAGE(PG8_SA(1, 0), cA + kstep, voffA); PG8_STAGE(PG8_SB(1, 1), cB + hB + kstep, voffB);
;     PG8_WAIT_V(6); PG8_BAR;
; __device__ void panel_outb(const Params& p, int r0) {
;     ...
;         const float rstd = rsqrtf(v * (1.f / 128.f) + 1e-5f);
;         float ov[8];
; #pragma unroll
;         for (int e = 0; e < 8; ++e) ov[e] = (hv[e] * rstd * gg[e] + sk[e] * x[e]) * silu(z[e]);
;         u32x4 w; w.x = cvt_pk(ov[0], ov[1]); w.y = cvt_pk(ov[2], ov[3]); w.z = cvt_pk(ov[4], ov[5]); w.w = cvt_pk(ov[6], ov[7]);
;         *(u32x4*)(CAT0 + r * 1024 + 512 + col) = w;
	v_mul_f32_e32 v6, v59, v49
	v_add_f32_e32 v4, 1.0, v4
	v_rcp_f32_e32 v42, v4
	v_mul_f32_e32 v4, 0xbfb8aa3b, v16
	v_exp_f32_e32 v4, v4
	v_pk_mul_f32 v[20:21], v[42:43], v[20:21]
	s_nop 0
	v_fma_f32 v12, v2, v6, v21
	v_add_f32_e32 v4, 1.0, v4
	v_rcp_f32_e32 v6, v4
	v_mul_f32_e32 v4, v20, v12
	v_lshlrev_b32_e32 v20, 16, v22
	v_mul_f32_e32 v12, v58, v49
	v_pk_mul_f32 v[16:17], v[6:7], v[16:17]
	v_mul_f32_e32 v6, 0xbfb8aa3b, v20
	v_exp_f32_e32 v6, v6
	v_fma_f32 v12, v3, v12, v17
	v_mul_f32_e32 v42, v16, v12
	v_and_b32_e32 v16, 0xffff0000, v22
	v_add_f32_e32 v6, 1.0, v6
	v_rcp_f32_e32 v44, v6
	v_mul_f32_e32 v6, 0xbfb8aa3b, v16
	v_exp_f32_e32 v6, v6
	v_lshlrev_b32_e32 v21, 16, v18
	v_mul_f32_e32 v12, v61, v49
	v_pk_mul_f32 v[20:21], v[44:45], v[20:21]
	v_add_f32_e32 v6, 1.0, v6
	v_fma_f32 v14, v8, v12, v21
	v_rcp_f32_e32 v12, v6
	v_mul_f32_e32 v6, v20, v14
	v_and_b32_e32 v17, 0xffff0000, v18
	v_lshlrev_b32_e32 v20, 16, v23
	v_pk_mul_f32 v[16:17], v[12:13], v[16:17]
	v_mul_f32_e32 v12, 0xbfb8aa3b, v20
	v_exp_f32_e32 v12, v12
	v_mul_f32_e32 v14, v60, v49
	v_fma_f32 v14, v9, v14, v17
	v_mul_f32_e32 v18, v16, v14
	v_add_f32_e32 v12, 1.0, v12
	v_and_b32_e32 v16, 0xffff0000, v23
	v_rcp_f32_e32 v46, v12
	v_mul_f32_e32 v12, 0xbfb8aa3b, v16
	v_exp_f32_e32 v12, v12
	v_lshlrev_b32_e32 v21, 16, v19
	v_mul_f32_e32 v14, v63, v49
	v_pk_mul_f32 v[20:21], v[46:47], v[20:21]
	v_add_f32_e32 v12, 1.0, v12
	v_fma_f32 v17, v10, v14, v21
	v_rcp_f32_e32 v14, v12
	v_mul_f32_e32 v12, v20, v17
	v_and_b32_e32 v17, 0xffff0000, v19
	v_mul_f32_e32 v20, v62, v49
	v_pk_mul_f32 v[16:17], v[14:15], v[16:17]
	s_nop 0
	v_fma_f32 v14, v11, v20, v17
	v_mul_f32_e32 v14, v16, v14
	v_cvt_pk_bf16_f32 v16, v40, v64
	v_cvt_pk_bf16_f32 v17, v4, v42
	v_cvt_pk_bf16_f32 v18, v6, v18
	v_cvt_pk_bf16_f32 v19, v12, v14
	global_store_dwordx4 v[38:39], v[16:19], off
	s_waitcnt vmcnt(2)
	v_mov_b64_e32 v[20:21], v[50:51]
	v_lshl_add_u64 v[38:39], v[38:39], 0, s[4:5]
	s_waitcnt vmcnt(1)
	v_mov_b64_e32 v[16:17], v[54:55]
	v_mov_b64_e32 v[18:19], v[56:57]
	v_mov_b64_e32 v[22:23], v[52:53]
	s_cbranch_scc1 .LBB0_372
	v_mov_b32_e32 v0, v176
	s_barrier
	s_mov_b32 s3, 0x1fffe0
	v_lshlrev_b32_e32 v1, 4, v0
	v_add_u32_e32 v2, 0x2000, v1
	v_ashrrev_i32_e32 v3, 31, v2
	v_lshrrev_b32_e32 v3, 22, v3
	v_add_u32_e32 v3, v2, v3
	v_ashrrev_i32_e32 v3, 10, v3
	v_mul_i32_i24_e32 v4, 0x400, v3
	v_sub_u32_e32 v2, v2, v4
	v_lshrrev_b32_e32 v4, 4, v2
	v_bitop3_b32 v2, v4, v2, 32 bitop3:0x6c
	v_ashrrev_i32_e32 v4, 31, v2
	v_lshrrev_b32_e32 v4, 26, v4
	v_add_u32_e32 v4, v2, v4
	v_lshlrev_b32_e32 v6, 3, v3
	v_ashrrev_i32_e32 v5, 6, v4
	v_and_b32_e32 v6, -16, v6
	v_and_b32_e32 v4, 0xc0, v4
	v_add_u32_e32 v6, v5, v6
	v_sub_u32_e32 v2, v2, v4
	v_mov_b32_e32 v4, 1
	v_and_b32_e32 v5, 3, v5
	v_lshrrev_b32_e32 v7, 2, v6
	v_lshlrev_b32_e32 v8, 1, v6
	v_lshlrev_b32_e32 v3, 5, v3
	v_ashrrev_i16_sdwa v2, v4, sext(v2) dst_sel:DWORD dst_unused:UNUSED_PAD src0_sel:DWORD src1_sel:BYTE_0
	v_and_or_b32 v5, v6, s3, v5
	v_and_b32_e32 v7, 4, v7
	v_and_b32_e32 v8, 24, v8
	v_and_b32_e32 v3, 32, v3
	v_bfe_i32 v2, v2, 0, 16
	v_or3_b32 v5, v5, v7, v8
	v_add_lshl_u32 v2, v3, v2, 1
	v_lshl_add_u32 v144, v5, 11, v2
	v_lshl_add_u32 v146, v6, 11, v2
	v_bfe_i32 v2, v0, 27, 1
	v_lshrrev_b32_e32 v2, 22, v2
	v_add_u32_e32 v2, v1, v2
	v_and_b32_e32 v2, 0xfffffc00, v2
	v_sub_u32_e32 v1, v1, v2
	v_lshrrev_b32_e32 v2, 4, v1
	v_ashrrev_i32_e32 v5, 31, v0
	v_bitop3_b32 v1, v2, v1, 32 bitop3:0x6c
	v_lshrrev_b32_e32 v5, 26, v5
	v_ashrrev_i32_e32 v2, 31, v1
	v_add_u32_e32 v5, v0, v5
	v_lshrrev_b32_e32 v2, 26, v2
	v_ashrrev_i32_e32 v5, 6, v5
	v_add_u32_e32 v2, v1, v2
	v_lshlrev_b32_e32 v6, 3, v5
	v_ashrrev_i32_e32 v3, 6, v2
	v_and_b32_e32 v6, -16, v6
	v_and_b32_e32 v2, 0xc0, v2
	s_add_u32 s0, s78, 0x18680000
	v_readfirstlane_b32 s25, v0
	v_add_u32_e32 v6, v3, v6
	v_sub_u32_e32 v1, v1, v2
	s_addc_u32 s1, s79, 0
	s_ashr_i32 s13, s25, 6
	v_and_b32_e32 v3, 3, v3
	v_lshrrev_b32_e32 v7, 2, v6
	v_lshlrev_b32_e32 v8, 1, v6
	v_lshlrev_b32_e32 v5, 5, v5
	v_ashrrev_i16_sdwa v1, v4, sext(v1) dst_sel:DWORD dst_unused:UNUSED_PAD src0_sel:DWORD src1_sel:BYTE_0
	s_lshl_b32 s26, s13, 10
	v_and_or_b32 v3, v6, s3, v3
	v_and_b32_e32 v7, 4, v7
	v_and_b32_e32 v8, 24, v8
	v_and_b32_e32 v5, 32, v5
	v_bfe_i32 v1, v1, 0, 16
	v_or3_b32 v3, v3, v7, v8
	v_add_lshl_u32 v1, v5, v1, 1
	s_add_i32 s27, s26, 0
	v_lshl_add_u32 v148, v3, 11, v1
	s_mov_b64 s[10:11], s[0:1]
	s_add_i32 m0, s27, 0x10000
	s_ashr_i32 s3, s2, 31
	s_ashr_i32 s12, s25, 8
	global_load_lds_dwordx4 v148, s[10:11]
	s_add_i32 m0, s27, 0x12000
	s_lshl_b64 s[4:5], s[2:3], 19
	global_load_lds_dwordx4 v144, s[10:11]
	v_readlane_b32 s10, v254, 46
	v_readlane_b32 s11, v254, 47
	s_add_u32 s10, s10, s4
	s_addc_u32 s11, s11, s5
	v_lshl_add_u32 v150, v6, 11, v1
	s_mov_b64 s[14:15], s[10:11]
	s_mov_b32 m0, s27
	s_add_i32 s28, s27, 0x2000
	v_mov_b32_e32 v153, 0
	global_load_lds_dwordx4 v150, s[14:15]
	s_mov_b32 m0, s28
	s_mov_b32 s43, 0
	global_load_lds_dwordx4 v146, s[14:15]
	s_add_u32 s14, s78, 0x186c0000
	s_addc_u32 s15, s79, 0
	s_add_i32 m0, s27, 0x14000
	v_mov_b32_e32 v149, v153
	global_load_lds_dwordx4 v148, s[14:15]
	s_add_i32 m0, s27, 0x16000
	v_mov_b32_e32 v145, v153
	global_load_lds_dwordx4 v144, s[14:15]
	s_add_u32 s14, s10, 0x40000
	s_addc_u32 s15, s11, 0
	s_add_i32 s29, s27, 0x4000
	s_mov_b32 m0, s29
	s_add_i32 s30, s27, 0x6000
	v_mov_b32_e32 v151, v153
	global_load_lds_dwordx4 v150, s[14:15]
	s_mov_b32 m0, s30
	s_cmp_lg_u32 s12, 1
	global_load_lds_dwordx4 v146, s[14:15]
	v_mov_b32_e32 v147, v153
	s_cbranch_scc1 .LBB0_375
	s_barrier

; __device__ __forceinline__ float bflo(unsigned w) { return __uint_as_float(w << 16); }
; __device__ __forceinline__ float bfhi(unsigned w) { return __uint_as_float(w & 0xffff0000u); }
; template <int OUT_F32> __device__ void panel_ln(const bf16_t* Y, const float* xp, const float* xs, const float* g, const float* b, void* dst, int r0) {
;     ...
;     for (int it = 0; it < 32; ++it) {
;         const size_t r = (size_t)r0 + it * 8 + wid;
;         float v[2][8]; float s = 0.f;
; #pragma unroll
;         for (int i = 0; i < 2; ++i) { const u32x4 w = wy[i];
;             v[i][0] = bflo(w.x); v[i][1] = bfhi(w.x); v[i][2] = bflo(w.y); v[i][3] = bfhi(w.y); v[i][4] = bflo(w.z); v[i][5] = bfhi(w.z); v[i][6] = bflo(w.w); v[i][7] = bfhi(w.w);
;             if (!OUT_F32) {
; #pragma unroll
;                 for (int e = 0; e < 4; ++e) { v[i][e] += wx[i][0][e] * ALPHA; v[i][4 + e] += wx[i][1][e] * ALPHA; } }
; #pragma unroll
;             for (int e = 0; e < 8; ++e) s += v[i][e]; }
;         LN_LOAD((it + 1 < 32) ? it + 1 : it);
; #pragma unroll
;         for (int off = 1; off < 64; off <<= 1) s += __shfl_xor(s, off);
;         const float mu = s * (1.f / 1024.f); float q = 0.f;
; #pragma unroll
;         for (int i = 0; i < 2; ++i)
; #pragma unroll
;             for (int e = 0; e < 8; ++e) { v[i][e] -= mu; q += v[i][e] * v[i][e]; }
; #pragma unroll
;         for (int off = 1; off < 64; off <<= 1) q += __shfl_xor(q, off);
;         const float rstd = rsqrtf(q * (1.f / 1024.f) + 1e-5f);
.LBB0_382:
	s_waitcnt vmcnt(3)
	v_lshlrev_b32_e32 v51, 16, v12
	v_and_b32_e32 v72, 0xffff0000, v12
	s_waitcnt vmcnt(2)
	v_lshlrev_b32_e32 v79, 16, v28
	v_and_b32_e32 v80, 0xffff0000, v28
	v_lshlrev_b32_e32 v81, 16, v29
	v_lshl_add_u64 v[24:25], v[38:39], 0, s[12:13]
	v_lshl_add_u64 v[26:27], v[40:41], 0, s[12:13]
	v_cmp_gt_u64_e32 vcc, s[0:1], v[42:43]
	v_fmac_f32_e32 v51, 0x3fb504f3, v8
	v_lshlrev_b32_e32 v73, 16, v13
	v_and_b32_e32 v65, 0xffff0000, v31
	v_lshlrev_b32_e32 v64, 16, v31
	v_and_b32_e32 v67, 0xffff0000, v30
	v_lshlrev_b32_e32 v66, 16, v30
	v_fmac_f32_e32 v72, 0x3fb504f3, v9
	s_waitcnt vmcnt(0)
	v_fmac_f32_e32 v79, 0x3fb504f3, v0
	v_fmac_f32_e32 v80, 0x3fb504f3, v1
	v_fmac_f32_e32 v81, 0x3fb504f3, v2
	v_cndmask_b32_e32 v1, v25, v27, vcc
	v_cndmask_b32_e32 v0, v24, v26, vcc
	v_add_f32_e32 v2, 0, v51
	v_and_b32_e32 v74, 0xffff0000, v13
	v_lshlrev_b32_e32 v75, 16, v14
	v_and_b32_e32 v76, 0xffff0000, v14
	v_lshlrev_b32_e32 v77, 16, v15
	v_and_b32_e32 v78, 0xffff0000, v15
	v_and_b32_e32 v82, 0xffff0000, v29
	v_fmac_f32_e32 v73, 0x3fb504f3, v10
	v_pk_fma_f32 v[22:23], v[22:23], s[14:15], v[64:65] op_sel_hi:[1,0,1]
	v_pk_fma_f32 v[20:21], v[20:21], s[14:15], v[66:67] op_sel_hi:[1,0,1]
	v_lshl_add_u64 v[64:65], v[0:1], 0, v[36:37]
	v_add_f32_e32 v66, v72, v2
	global_load_dwordx4 v[12:15], v[44:45], off
	global_load_dwordx4 v[16:19], v[44:45], off offset:1024
	global_load_dwordx4 v[28:31], v[32:33], off offset:16
	global_load_dwordx4 v[52:55], v[32:33], off
	global_load_dwordx4 v[56:59], v[34:35], off offset:16
	global_load_dwordx4 v[60:63], v[34:35], off
	v_fmac_f32_e32 v75, 0x3fb504f3, v4
	v_fmac_f32_e32 v76, 0x3fb504f3, v5
	v_fmac_f32_e32 v77, 0x3fb504f3, v6
	v_fmac_f32_e32 v74, 0x3fb504f3, v11
	v_fmac_f32_e32 v78, 0x3fb504f3, v7
	v_fmac_f32_e32 v82, 0x3fb504f3, v3
	global_load_dwordx4 v[4:7], v[64:65], off offset:16 nt
	global_load_dwordx4 v[8:11], v[64:65], off nt
	global_load_dwordx4 v[24:27], v[64:65], off offset:2064 nt
	global_load_dwordx4 v[0:3], v[64:65], off offset:2048 nt
	v_add_f32_e32 v64, v73, v66
	v_add_f32_e32 v64, v74, v64
	v_add_f32_e32 v64, v75, v64
	v_add_f32_e32 v64, v76, v64
	v_add_f32_e32 v64, v77, v64
	v_add_f32_e32 v64, v78, v64
	v_add_f32_e32 v64, v79, v64
	v_add_f32_e32 v64, v80, v64
	v_add_f32_e32 v64, v81, v64
	v_add_f32_e32 v64, v82, v64
	v_add_f32_e32 v64, v20, v64
	v_add_f32_e32 v64, v21, v64
	v_add_f32_e32 v64, v22, v64
	v_add_f32_e32 v64, v23, v64
	s_add_u32 s12, s12, 0x8000
	s_addc_u32 s13, s13, 0
	v_lshl_add_u64 v[42:43], v[42:43], 0, 8
	v_lshl_add_u64 v[44:45], v[44:45], 0, s[10:11]
	s_nop 1
	v_add_f32_dpp v64, v64, v64 quad_perm:[1,0,3,2] row_mask:0xf bank_mask:0xf
	s_cmp_lg_u32 s12, 0xf8000
	s_nop 1
	v_add_f32_dpp v64, v64, v64 quad_perm:[2,3,0,1] row_mask:0xf bank_mask:0xf
	s_nop 1
	v_add_f32_dpp v64, v64, v64 row_half_mirror row_mask:0xf bank_mask:0xf
	s_nop 1
	v_add_f32_dpp v64, v64, v64 row_mirror row_mask:0xf bank_mask:0xf
	v_mov_b32_e32 v65, v64
	s_nop 1
	v_permlane16_swap_b32_e32 v65, v64
	v_add_f32_e32 v64, v64, v65
	v_mov_b32_e32 v65, v64
	s_nop 1
	v_permlane32_swap_b32_e32 v65, v64
	v_add_f32_e32 v65, v64, v65
	v_fmac_f32_e32 v72, 0xba800000, v65
	v_mul_f32_e32 v64, 0x3a800000, v65
	v_fmac_f32_e32 v51, 0xba800000, v65
	v_fmac_f32_e32 v73, 0xba800000, v65
	v_fmac_f32_e32 v74, 0xba800000, v65
	v_fmac_f32_e32 v75, 0xba800000, v65
	v_fmac_f32_e32 v76, 0xba800000, v65
	v_fmac_f32_e32 v77, 0xba800000, v65
	v_fmac_f32_e32 v78, 0xba800000, v65
	v_fmac_f32_e32 v79, 0xba800000, v65
	v_fmac_f32_e32 v80, 0xba800000, v65
	v_fmac_f32_e32 v81, 0xba800000, v65
	v_fmac_f32_e32 v82, 0xba800000, v65
	v_mul_f32_e32 v65, v72, v72
	v_pk_add_f32 v[68:69], v[20:21], v[64:65] op_sel_hi:[1,0] neg_lo:[0,1] neg_hi:[0,1]
	v_pk_add_f32 v[70:71], v[22:23], v[64:65] op_sel_hi:[1,0] neg_lo:[0,1] neg_hi:[0,1]
	v_fmac_f32_e32 v65, v51, v51
	v_fmac_f32_e32 v65, v73, v73
	v_fmac_f32_e32 v65, v74, v74
	v_fmac_f32_e32 v65, v75, v75
	v_fmac_f32_e32 v65, v76, v76
	v_fmac_f32_e32 v65, v77, v77
	v_fmac_f32_e32 v65, v78, v78
	v_fmac_f32_e32 v65, v79, v79
	v_fmac_f32_e32 v65, v80, v80
	v_fmac_f32_e32 v65, v81, v81
	v_pk_mul_f32 v[20:21], v[68:69], v[68:69]
	v_fmac_f32_e32 v65, v82, v82
	v_add_f32_e32 v20, v20, v65
	v_pk_mul_f32 v[22:23], v[70:71], v[70:71]
	v_add_f32_e32 v20, v21, v20
	v_add_f32_e32 v20, v22, v20
	v_add_f32_e32 v20, v23, v20
	s_nop 1
	v_add_f32_dpp v20, v20, v20 quad_perm:[1,0,3,2] row_mask:0xf bank_mask:0xf
	s_nop 1
	v_add_f32_dpp v20, v20, v20 quad_perm:[2,3,0,1] row_mask:0xf bank_mask:0xf
	s_nop 1
	v_add_f32_dpp v20, v20, v20 row_half_mirror row_mask:0xf bank_mask:0xf
	s_nop 1
	v_add_f32_dpp v20, v20, v20 row_mirror row_mask:0xf bank_mask:0xf
	v_mov_b32_e32 v21, v20
	s_nop 1
	v_permlane16_swap_b32_e32 v21, v20
	v_add_f32_e32 v20, v20, v21
	v_mov_b32_e32 v21, v20
	s_nop 1
	v_permlane32_swap_b32_e32 v21, v20
	v_add_f32_e32 v20, v20, v21
	v_fmamk_f32 v20, v20, 0x3a800000, v50
	v_mul_f32_e32 v21, 0x4b800000, v20
	v_cmp_gt_f32_e32 vcc, s15, v20
	s_nop 1
	v_cndmask_b32_e32 v20, v20, v21, vcc
	v_rsq_f32_e32 v20, v20
	s_nop 0
	v_mul_f32_e32 v21, 0x45800000, v20
	v_cndmask_b32_e32 v83, v20, v21, vcc
	v_mul_f32_e32 v20, v51, v83
	v_mul_f32_e32 v21, v75, v83
	v_mul_f32_e32 v22, v72, v83
	v_mul_f32_e32 v23, v76, v83
	v_mul_f32_e32 v51, v73, v83
	v_mul_f32_e32 v64, v77, v83
	v_mul_f32_e32 v65, v74, v83
	v_mul_f32_e32 v66, v78, v83
	s_waitcnt vmcnt(4)
	v_fma_f32 v20, v52, v20, v60
	v_fma_f32 v28, v28, v21, v56
	v_fma_f32 v21, v53, v22, v61
	v_fma_f32 v22, v29, v23, v57
	v_fma_f32 v23, v54, v51, v62
	v_fma_f32 v29, v30, v64, v58
	v_fmac_f32_e32 v63, v55, v65
	v_fmac_f32_e32 v59, v31, v66
	v_cvt_pk_bf16_f32 v20, v20, v21
	v_cvt_pk_bf16_f32 v21, v23, v63
	v_cvt_pk_bf16_f32 v22, v28, v22
	v_cvt_pk_bf16_f32 v23, v29, v59
	global_store_dwordx4 v[46:47], v[20:23], off offset:-1024
	global_load_dwordx4 v[52:55], v[32:33], off offset:2064
	global_load_dwordx4 v[56:59], v[32:33], off offset:2048
	global_load_dwordx4 v[60:63], v[34:35], off offset:2048
	global_load_dwordx4 v[64:67], v[34:35], off offset:2064
	v_mul_f32_e32 v51, v79, v83
	v_mul_f32_e32 v68, v68, v83
	v_mul_f32_e32 v72, v80, v83
	v_mul_f32_e32 v69, v69, v83
	v_mul_f32_e32 v73, v81, v83
	v_mov_b64_e32 v[30:31], v[18:19]
	s_waitcnt vmcnt(6)
	v_mov_b64_e32 v[20:21], v[24:25]
	v_mul_f32_e32 v70, v70, v83
	v_mul_f32_e32 v74, v82, v83
	v_mul_f32_e32 v71, v71, v83
	v_mov_b64_e32 v[28:29], v[16:17]
	v_mov_b64_e32 v[22:23], v[26:27]
	s_waitcnt vmcnt(1)
	v_fma_f32 v51, v56, v51, v60
	s_waitcnt vmcnt(0)
	v_fma_f32 v56, v52, v68, v64
	v_fma_f32 v52, v57, v72, v61
	v_fma_f32 v57, v53, v69, v65
	v_fma_f32 v53, v58, v73, v62
	v_fma_f32 v58, v54, v70, v66
	v_fmac_f32_e32 v63, v59, v74
	v_fmac_f32_e32 v67, v55, v71
	v_cvt_pk_bf16_f32 v52, v51, v52
	v_cvt_pk_bf16_f32 v53, v53, v63
	v_cvt_pk_bf16_f32 v54, v56, v57
	v_cvt_pk_bf16_f32 v55, v58, v67
	global_store_dwordx4 v[46:47], v[52:55], off
	v_lshl_add_u64 v[46:47], v[46:47], 0, s[16:17]
	s_cbranch_scc1 .LBB0_382
; __device__ __forceinline__ unsigned cvt_pk(float lo, float hi) { unsigned r; asm volatile("v_cvt_pk_bf16_f32 %0, %1, %2" : "=v"(r) : "v"(lo), "v"(hi)); return r; }
; __device__ __forceinline__ float bflo(unsigned w) { return __uint_as_float(w << 16); }
; __device__ __forceinline__ float bfhi(unsigned w) { return __uint_as_float(w & 0xffff0000u); }
; template <int OUT_F32> __device__ void panel_ln(const bf16_t* Y, const float* xp, const float* xs, const float* g, const float* b, void* dst, int r0) {
;     ...
;         const size_t r = (size_t)r0 + it * 8 + wid;
;         float v[2][8]; float s = 0.f;
; #pragma unroll
;         for (int i = 0; i < 2; ++i) { const u32x4 w = wy[i];
;             v[i][0] = bflo(w.x); v[i][1] = bfhi(w.x); v[i][2] = bflo(w.y); v[i][3] = bfhi(w.y); v[i][4] = bflo(w.z); v[i][5] = bfhi(w.z); v[i][6] = bflo(w.w); v[i][7] = bfhi(w.w);
;             if (!OUT_F32) {
; #pragma unroll
;                 for (int e = 0; e < 4; ++e) { v[i][e] += wx[i][0][e] * ALPHA; v[i][4 + e] += wx[i][1][e] * ALPHA; } }
; #pragma unroll
;             for (int e = 0; e < 8; ++e) s += v[i][e]; }
;         LN_LOAD((it + 1 < 32) ? it + 1 : it);
; #pragma unroll
;         for (int off = 1; off < 64; off <<= 1) s += __shfl_xor(s, off);
;         const float mu = s * (1.f / 1024.f); float q = 0.f;
; #pragma unroll
;         for (int i = 0; i < 2; ++i)
; #pragma unroll
;             for (int e = 0; e < 8; ++e) { v[i][e] -= mu; q += v[i][e] * v[i][e]; }
; #pragma unroll
;         for (int off = 1; off < 64; off <<= 1) q += __shfl_xor(q, off);
;         const float rstd = rsqrtf(q * (1.f / 1024.f) + 1e-5f);
; #pragma unroll
;         for (int i = 0; i < 2; ++i) { const int c = i * 512 + lane * 8; const f32x4 g0 = *(const f32x4*)(g + c), g1 = *(const f32x4*)(g + c + 4), b0 = *(const f32x4*)(b + c), b1 = *(const f32x4*)(b + c + 4);
;             f32x4 o0, o1;
; #pragma unroll
;             for (int e = 0; e < 4; ++e) { o0[e] = v[i][e] * rstd * g0[e] + b0[e]; o1[e] = v[i][4 + e] * rstd * g1[e] + b1[e]; }
;             if (OUT_F32) { __builtin_nontemporal_store(o0, (f32x4*)((float*)dst + r * 1024 + c)); __builtin_nontemporal_store(o1, (f32x4*)((float*)dst + r * 1024 + c + 4)); }
;             else { u32x4 w; w.x = cvt_pk(o0[0], o0[1]); w.y = cvt_pk(o0[2], o0[3]); w.z = cvt_pk(o1[0], o1[1]); w.w = cvt_pk(o1[2], o1[3]); *(u32x4*)((bf16_t*)dst + r * 1024 + c) = w; } }
	v_lshlrev_b32_e32 v28, 16, v12
	v_and_b32_e32 v29, 0xffff0000, v12
	v_lshlrev_b32_e32 v36, 16, v14
	v_fmac_f32_e32 v28, 0x3fb504f3, v8
	v_lshlrev_b32_e32 v30, 16, v13
	v_fmac_f32_e32 v36, 0x3fb504f3, v4
	v_fmac_f32_e32 v29, 0x3fb504f3, v9
	v_add_f32_e32 v4, 0, v28
	v_and_b32_e32 v31, 0xffff0000, v13
	v_fmac_f32_e32 v30, 0x3fb504f3, v10
	v_add_f32_e32 v4, v29, v4
	v_fmac_f32_e32 v31, 0x3fb504f3, v11
	v_add_f32_e32 v4, v30, v4
	v_and_b32_e32 v37, 0xffff0000, v14
	v_add_f32_e32 v4, v31, v4
	v_lshlrev_b32_e32 v38, 16, v15
	v_fmac_f32_e32 v37, 0x3fb504f3, v5
	v_add_f32_e32 v4, v36, v4
	v_and_b32_e32 v39, 0xffff0000, v15
	v_fmac_f32_e32 v38, 0x3fb504f3, v6
	v_add_f32_e32 v4, v37, v4
	v_fmac_f32_e32 v39, 0x3fb504f3, v7
	v_add_f32_e32 v4, v38, v4
	v_lshlrev_b32_e32 v40, 16, v16
	v_add_f32_e32 v4, v39, v4
	v_and_b32_e32 v41, 0xffff0000, v16
	v_fmac_f32_e32 v40, 0x3fb504f3, v0
	v_lshlrev_b32_e32 v42, 16, v17
	v_fmac_f32_e32 v41, 0x3fb504f3, v1
	v_add_f32_e32 v0, v40, v4
	v_and_b32_e32 v43, 0xffff0000, v17
	v_fmac_f32_e32 v42, 0x3fb504f3, v2
	v_add_f32_e32 v0, v41, v0
	v_fmac_f32_e32 v43, 0x3fb504f3, v3
	v_add_f32_e32 v0, v42, v0
	s_mov_b32 s0, 0x3fb504f3
	v_add_f32_e32 v2, v43, v0
	v_and_b32_e32 v1, 0xffff0000, v19
	v_lshlrev_b32_e32 v0, 16, v19
	v_pk_fma_f32 v[16:17], v[26:27], s[0:1], v[0:1] op_sel_hi:[1,0,1]
	v_and_b32_e32 v1, 0xffff0000, v18
	v_lshlrev_b32_e32 v0, 16, v18
	v_pk_fma_f32 v[18:19], v[24:25], s[0:1], v[0:1] op_sel_hi:[1,0,1]
	s_mov_b32 s0, 0x800000
	v_add_f32_e32 v0, v18, v2
	v_add_f32_e32 v0, v19, v0
	v_add_f32_e32 v0, v16, v0
	v_add_f32_e32 v0, v17, v0
	v_mov_b32_e32 v129, 0
	s_mov_b32 s10, 0x1fffe0
	s_mov_b32 s29, 0
	v_mov_b32_e32 v135, v129
	s_nop 1
	v_add_f32_dpp v0, v0, v0 quad_perm:[1,0,3,2] row_mask:0xf bank_mask:0xf
	v_mov_b32_e32 v137, v129
	v_mov_b32_e32 v133, v129
	s_nop 1
	v_add_f32_dpp v0, v0, v0 quad_perm:[2,3,0,1] row_mask:0xf bank_mask:0xf
	s_nop 1
	v_add_f32_dpp v0, v0, v0 row_half_mirror row_mask:0xf bank_mask:0xf
	s_nop 1
	v_add_f32_dpp v0, v0, v0 row_mirror row_mask:0xf bank_mask:0xf
	v_mov_b32_e32 v1, v0
	s_nop 1
	v_permlane16_swap_b32_e32 v1, v0
	v_add_f32_e32 v0, v0, v1
	v_mov_b32_e32 v1, v0
	v_mov_b32_e32 v21, v0
	s_nop 1
	v_permlane32_swap_b32_e32 v1, v21
	v_add_f32_e32 v21, v21, v1
	global_load_dwordx4 v[0:3], v[32:33], off offset:16
	global_load_dwordx4 v[4:7], v[32:33], off
	global_load_dwordx4 v[8:11], v[34:35], off offset:16
	global_load_dwordx4 v[12:15], v[34:35], off
	v_fmac_f32_e32 v29, 0xba800000, v21
	v_fmac_f32_e32 v28, 0xba800000, v21
	v_mul_f32_e32 v24, v29, v29
	v_fmac_f32_e32 v24, v28, v28
	v_fmac_f32_e32 v30, 0xba800000, v21
	v_fmac_f32_e32 v24, v30, v30
	v_fmac_f32_e32 v31, 0xba800000, v21
	v_fmac_f32_e32 v24, v31, v31
	v_fmac_f32_e32 v36, 0xba800000, v21
	v_fmac_f32_e32 v24, v36, v36
	v_fmac_f32_e32 v37, 0xba800000, v21
	v_fmac_f32_e32 v24, v37, v37
	v_fmac_f32_e32 v38, 0xba800000, v21
	v_fmac_f32_e32 v24, v38, v38
	v_fmac_f32_e32 v39, 0xba800000, v21
	v_fmac_f32_e32 v24, v39, v39
	v_fmac_f32_e32 v40, 0xba800000, v21
	v_fmac_f32_e32 v24, v40, v40
	v_fmac_f32_e32 v41, 0xba800000, v21
	v_mul_f32_e32 v20, 0x3a800000, v21
	v_fmac_f32_e32 v24, v41, v41
	v_fmac_f32_e32 v42, 0xba800000, v21
	v_fmac_f32_e32 v24, v42, v42
	v_fmac_f32_e32 v43, 0xba800000, v21
	v_pk_add_f32 v[18:19], v[18:19], v[20:21] op_sel_hi:[1,0] neg_lo:[0,1] neg_hi:[0,1]
	v_fmac_f32_e32 v24, v43, v43
	v_pk_mul_f32 v[22:23], v[18:19], v[18:19]
	s_nop 0
	v_add_f32_e32 v21, v22, v24
	v_add_f32_e32 v22, v23, v21
	v_pk_add_f32 v[20:21], v[16:17], v[20:21] op_sel_hi:[1,0] neg_lo:[0,1] neg_hi:[0,1]
	s_nop 0
	v_pk_mul_f32 v[16:17], v[20:21], v[20:21]
	s_nop 0
	v_add_f32_e32 v16, v16, v22
	v_add_f32_e32 v16, v17, v16
	s_nop 1
	v_add_f32_dpp v16, v16, v16 quad_perm:[1,0,3,2] row_mask:0xf bank_mask:0xf
	s_nop 1
	v_add_f32_dpp v16, v16, v16 quad_perm:[2,3,0,1] row_mask:0xf bank_mask:0xf
	s_nop 1
	v_add_f32_dpp v16, v16, v16 row_half_mirror row_mask:0xf bank_mask:0xf
	s_nop 1
	v_add_f32_dpp v16, v16, v16 row_mirror row_mask:0xf bank_mask:0xf
	v_mov_b32_e32 v17, v16
	s_nop 1
	v_permlane16_swap_b32_e32 v17, v16
	v_add_f32_e32 v16, v16, v17
	v_mov_b32_e32 v17, v16
	s_nop 1
	v_permlane32_swap_b32_e32 v17, v16
	v_add_f32_e32 v16, v16, v17
	v_mov_b32_e32 v17, 0x3727c5ac
	v_fmac_f32_e32 v17, 0x3a800000, v16
	v_mul_f32_e32 v16, 0x4b800000, v17
	v_cmp_gt_f32_e32 vcc, s0, v17
	s_mov_b64 s[0:1], 0x7c000
	s_nop 0
	v_cndmask_b32_e32 v16, v17, v16, vcc
	v_rsq_f32_e32 v16, v16
	s_nop 0
	v_mul_f32_e32 v17, 0x45800000, v16
	v_cndmask_b32_e32 v24, v16, v17, vcc
	v_lshl_add_u64 v[16:17], s[76:77], 0, v[130:131]
	v_lshl_add_u64 v[22:23], v[16:17], 0, s[0:1]
	v_mul_f32_e32 v16, v28, v24
	s_waitcnt vmcnt(0)
	v_fma_f32 v4, v4, v16, v12
	v_mul_f32_e32 v12, v36, v24
	v_fma_f32 v8, v0, v12, v8
	v_mul_f32_e32 v0, v29, v24
	v_fma_f32 v0, v5, v0, v13
	v_mul_f32_e32 v5, v37, v24
	v_fma_f32 v5, v1, v5, v9
	v_mul_f32_e32 v1, v30, v24
	v_fma_f32 v1, v6, v1, v14
	v_mul_f32_e32 v6, v38, v24
	v_fma_f32 v6, v2, v6, v10
	v_mul_f32_e32 v2, v31, v24
	v_fmac_f32_e32 v15, v7, v2
	v_mul_f32_e32 v2, v39, v24
	v_fmac_f32_e32 v11, v3, v2
	v_cvt_pk_bf16_f32 v0, v4, v0
	v_cvt_pk_bf16_f32 v1, v1, v15
	v_cvt_pk_bf16_f32 v2, v8, v5
	v_lshl_add_u64 v[4:5], v[22:23], 0, v[128:129]
	v_cvt_pk_bf16_f32 v3, v6, v11
	global_store_dwordx4 v[4:5], v[0:3], off
	global_load_dwordx4 v[2:5], v[32:33], off offset:2064
	s_nop 0
	global_load_dwordx4 v[6:9], v[32:33], off offset:2048
	global_load_dwordx4 v[10:13], v[34:35], off offset:2048
	global_load_dwordx4 v[14:17], v[34:35], off offset:2064
	v_mul_f32_e32 v25, v40, v24
	v_mul_f32_e32 v18, v18, v24
	v_mul_f32_e32 v26, v41, v24
	v_or_b32_e32 v128, 0x400, v128
	v_mul_f32_e32 v19, v19, v24
	v_mul_f32_e32 v27, v42, v24
	v_mov_b32_e32 v0, v176
	v_lshl_add_u64 v[22:23], v[22:23], 0, v[128:129]
	v_mul_f32_e32 v20, v20, v24
	v_mul_f32_e32 v28, v43, v24
	v_mul_f32_e32 v21, v21, v24
	v_mov_b32_e32 v1, 1
	s_add_u32 s0, s78, 0x18880000
	s_addc_u32 s1, s79, 0
	v_mov_b32_e32 v131, v129
	s_waitcnt vmcnt(1)
	v_fma_f32 v6, v6, v25, v10
	s_waitcnt vmcnt(0)
	v_fma_f32 v10, v2, v18, v14
	v_fma_f32 v2, v7, v26, v11
	v_fma_f32 v7, v3, v19, v15
	v_fma_f32 v3, v8, v27, v12
	v_cvt_pk_bf16_f32 v2, v6, v2
	v_fma_f32 v8, v4, v20, v16
	v_fmac_f32_e32 v13, v9, v28
	v_fmac_f32_e32 v17, v5, v21
	v_cvt_pk_bf16_f32 v3, v3, v13
	v_cvt_pk_bf16_f32 v4, v10, v7
	v_cvt_pk_bf16_f32 v5, v8, v17
	global_store_dwordx4 v[22:23], v[2:5], off
	s_barrier
; #define PG8_STAGE(bufoff, gbase, voff) do { const char* _gb = (const char*)(gbase); asm volatile("" : "+s"(_gb)); _Pragma("unroll") for (int _i = 0; _i < 2; ++_i) \
;         __builtin_amdgcn_global_load_lds((const unsigned*)(_gb + (voff)[_i]), (LAS unsigned*)(lds + (bufoff) + ldsw + _i * 8192), 16, 0, 0); } while (0)
; #define PG8_WAIT_V(n) asm volatile("s_waitcnt vmcnt(" #n ")" ::: "memory")
; #define PG8_BAR __builtin_amdgcn_s_barrier()
; template <class Epi, class Sched>
; __device__ __forceinline__ void gemm_phase(LAS unsigned char* lds, const Gemm g, const Sched& S, const Epi& E) {
;     ...
;     for (int i = 0; i < 2; ++i) { int R, C; stage_rc(tid * 16 + i * 8192, R, C); const int Rb = Epi::PERM ? ((R & ~31) + perm32(R & 31)) : R;
;         voffA[i] = (unsigned)(R * lda + C) * 2u; voffB[i] = (unsigned)(Rb * K + C) * 2u; }
;     const size_t kstep = (size_t)(BK * 2);
;     const size_t hA = (size_t)HALF * lda * 2, hB = (size_t)HALF * K * 2;
;     const size_t tA = 2 * hA, tB = 2 * hB;
;     const unsigned ldsw = (unsigned)wid * 1024u;
;     const int aoff = lds_byte(wr * 64 + fr, fq * 8), boff = lds_byte(wc * 32 + fr, fq * 8);
;     ...
;     Unit cur, nxt; int ui = 0;
;     if (!S.next(0, cur)) return;
;     f32x4 acc[2][2][4][2];
; #pragma unroll
;     for (int a = 0; a < 2; ++a)
; #pragma unroll
;         for (int b = 0; b < 2; ++b)
; #pragma unroll
;             for (int m = 0; m < 4; ++m)
; #pragma unroll
;                 for (int n = 0; n < 2; ++n) acc[a][b][m][n] = (f32x4){0.f, 0.f, 0.f, 0.f};
;     bf16x8 At[4][2], B0[2][2], B1[2][2];
;     const char* cA = (const char*)g.A + (size_t)cur.pm * tA; const char* cB = (const char*)g.Bt + (size_t)cur.pn * tB;
;     PG8_STAGE(PG8_SB(0, 0), cB, voffB); PG8_STAGE(PG8_SA(0, 0), cA, voffA); PG8_STAGE(PG8_SB(0, 1), cB + hB, voffB); PG8_STAGE(PG8_SA(0, 1), cA + hA, voffA);
;     if (wr == 1) PG8_BAR;
;     PG8_WAIT_V(4); PG8_BAR;
;     PG8_STAGE(PG8_SB(1, 0), cB + kstep, voffB); PG8_STAGE(PG8_SA(1, 0), cA + kstep, voffA); PG8_STAGE(PG8_SB(1, 1), cB + hB + kstep, voffB);
;     PG8_WAIT_V(6); PG8_BAR;
	s_nop 0
	v_lshlrev_b32_e32 v2, 4, v0
	v_add_u32_e32 v4, 0x2000, v2
	v_ashrrev_i32_e32 v5, 31, v4
	v_lshrrev_b32_e32 v5, 22, v5
	v_add_u32_e32 v5, v4, v5
	v_ashrrev_i32_e32 v5, 10, v5
	v_mul_i32_i24_e32 v6, 0x400, v5
	v_lshlrev_b32_e32 v7, 3, v5
	v_sub_u32_e32 v4, v4, v6
	v_and_b32_e32 v6, -16, v7
	v_lshrrev_b32_e32 v7, 4, v4
	v_bitop3_b32 v4, v7, v4, 32 bitop3:0x6c
	v_ashrrev_i32_e32 v7, 31, v4
	v_lshrrev_b32_e32 v7, 26, v7
	v_bfe_i32 v3, v0, 27, 1
	v_add_u32_e32 v7, v4, v7
	v_lshrrev_b32_e32 v3, 22, v3
	v_ashrrev_i32_e32 v8, 6, v7
	v_and_b32_e32 v7, 0xc0, v7
	v_add_u32_e32 v3, v2, v3
	v_sub_u32_e32 v4, v4, v7
	v_and_b32_e32 v3, 0xfffffc00, v3
	v_lshlrev_b32_e32 v5, 5, v5
	v_ashrrev_i16_sdwa v4, v1, sext(v4) dst_sel:DWORD dst_unused:UNUSED_PAD src0_sel:DWORD src1_sel:BYTE_0
	v_and_b32_e32 v5, 32, v5
	v_bfe_i32 v4, v4, 0, 16
	v_sub_u32_e32 v2, v2, v3
	v_add_lshl_u32 v4, v5, v4, 1
	v_lshrrev_b32_e32 v3, 4, v2
	v_ashrrev_i32_e32 v5, 31, v0
	v_add_u32_e32 v6, v8, v6
	v_and_b32_e32 v8, 3, v8
	v_bitop3_b32 v2, v3, v2, 32 bitop3:0x6c
	v_lshrrev_b32_e32 v5, 26, v5
	v_and_or_b32 v7, v6, s10, v8
	v_lshrrev_b32_e32 v8, 2, v6
	v_lshlrev_b32_e32 v9, 1, v6
	v_ashrrev_i32_e32 v3, 31, v2
	v_add_u32_e32 v5, v0, v5
	v_and_b32_e32 v8, 4, v8
	v_and_b32_e32 v9, 24, v9
	v_lshrrev_b32_e32 v3, 26, v3
	v_ashrrev_i32_e32 v5, 6, v5
	v_or3_b32 v7, v7, v8, v9
	v_lshl_add_u32 v132, v6, 11, v4
	v_add_u32_e32 v3, v2, v3
	v_lshlrev_b32_e32 v6, 3, v5
	v_lshl_add_u32 v130, v7, 11, v4
	v_ashrrev_i32_e32 v4, 6, v3
	v_and_b32_e32 v6, -16, v6
	v_and_b32_e32 v3, 0xc0, v3
	v_readfirstlane_b32 s22, v0
	v_add_u32_e32 v6, v4, v6
	v_sub_u32_e32 v2, v2, v3
	s_ashr_i32 s13, s22, 6
	v_and_b32_e32 v4, 3, v4
	v_lshrrev_b32_e32 v7, 2, v6
	v_lshlrev_b32_e32 v8, 1, v6
	v_lshlrev_b32_e32 v5, 5, v5
	v_ashrrev_i16_sdwa v1, v1, sext(v2) dst_sel:DWORD dst_unused:UNUSED_PAD src0_sel:DWORD src1_sel:BYTE_0
	s_lshl_b32 s23, s13, 10
	v_and_or_b32 v4, v6, s10, v4
	v_and_b32_e32 v7, 4, v7
	v_and_b32_e32 v8, 24, v8
	v_and_b32_e32 v5, 32, v5
	v_bfe_i32 v1, v1, 0, 16
	v_or3_b32 v4, v4, v7, v8
	v_add_lshl_u32 v1, v5, v1, 1
	s_add_i32 s25, s23, 0
	v_lshl_add_u32 v134, v4, 11, v1
	s_mov_b64 s[10:11], s[0:1]
	s_add_i32 m0, s25, 0x10000
	s_ashr_i32 s12, s22, 8
	v_lshl_add_u32 v136, v6, 11, v1
	global_load_lds_dwordx4 v134, s[10:11]
	s_add_i32 m0, s25, 0x12000
	s_nop 0
	global_load_lds_dwordx4 v130, s[10:11]
	s_add_u32 s10, s76, s4
	s_addc_u32 s11, s77, s5
	s_mov_b64 s[4:5], s[10:11]
	s_mov_b32 m0, s25
	s_add_i32 s26, s25, 0x2000
	s_nop 0
	global_load_lds_dwordx4 v136, s[4:5]
	s_mov_b32 m0, s26
	s_nop 0
	global_load_lds_dwordx4 v132, s[4:5]
	s_add_u32 s4, s78, 0x188c0000
	s_addc_u32 s5, s79, 0
	s_add_i32 m0, s25, 0x14000
	s_nop 0
	global_load_lds_dwordx4 v134, s[4:5]
	s_add_i32 m0, s25, 0x16000
	s_nop 0
	global_load_lds_dwordx4 v130, s[4:5]
	s_add_u32 s4, s10, 0x40000
	s_addc_u32 s5, s11, 0
	s_add_i32 s27, s25, 0x4000
	s_mov_b32 m0, s27
	s_add_i32 s28, s25, 0x6000
	s_cmp_lg_u32 s12, 1
	global_load_lds_dwordx4 v136, s[4:5]
	s_mov_b32 m0, s28
	s_nop 0
	global_load_lds_dwordx4 v132, s[4:5]
	s_cbranch_scc1 .LBB0_385
	s_barrier

; __device__ __forceinline__ unsigned cvt_pk(float lo, float hi) { unsigned r; asm volatile("v_cvt_pk_bf16_f32 %0, %1, %2" : "=v"(r) : "v"(lo), "v"(hi)); return r; }
; __device__ __forceinline__ float bflo(unsigned w) { return __uint_as_float(w << 16); }
; __device__ __forceinline__ float bfhi(unsigned w) { return __uint_as_float(w & 0xffff0000u); }
; __device__ void panel_qknorm(const Params& p, int r0) {
;     ...
;     for (int u = wid * 4 + sub; u < 512; u += 32) {
;         const int rl = u >> 1, hh = 8 + (u & 1); const size_t r = (size_t)r0 + rl;
;         const int t = (r < NPROMPT) ? (int)(r & 4095) : (int)((r - NPROMPT) & 2047);
;         const float pos = (float)(axis ? (t & 63) : (t >> 6));
;         bf16_t* base = P1 + r * LDP + (hh < 8 ? hh * 128 : 1024 + (hh - 8) * 128);
;         const float* gn = hh < 8 ? p.qng : p.kng;
;         const u32x2 w1 = *(const u32x2*)(base + d1), w2 = *(const u32x2*)(base + d2);
;         float x1[4] = {bflo(w1.x), bfhi(w1.x), bflo(w1.y), bfhi(w1.y)}, x2[4] = {bflo(w2.x), bfhi(w2.x), bflo(w2.y), bfhi(w2.y)};
;         float ss = 0.f;
; #pragma unroll
;         for (int e = 0; e < 4; ++e) ss += x1[e] * x1[e] + x2[e] * x2[e];
;         ss += __shfl_xor(ss, 1); ss += __shfl_xor(ss, 2); ss += __shfl_xor(ss, 4); ss += __shfl_xor(ss, 8);
;         const float rinv = rsqrtf(ss * (1.f / 128.f) + 1e-6f);
;         const f32x4 g1 = *(const f32x4*)(gn + d1), g2 = *(const f32x4*)(gn + d2);
;         float o1[4], o2[4];
; #pragma unroll
;         for (int e = 0; e < 4; ++e) { const float a = x1[e] * rinv * g1[e], bb = x2[e] * rinv * g2[e];
;             const float ang = pos * inv[e]; float sn, cs; __sincosf(ang, &sn, &cs);
;             o1[e] = a * cs - bb * sn; o2[e] = bb * cs + a * sn; }
;         u32x2 q1, q2; q1.x = cvt_pk(o1[0], o1[1]); q1.y = cvt_pk(o1[2], o1[3]); q2.x = cvt_pk(o2[0], o2[1]); q2.y = cvt_pk(o2[2], o2[3]);
;         *(u32x2*)(base + d1) = q1; *(u32x2*)(base + d2) = q2;
;     }
.LBB0_424:
	global_load_dwordx2 v[22:23], v[4:5], off
	global_load_dwordx2 v[24:25], v[4:5], off offset:64
	global_load_dwordx4 v[14:17], v[0:1], off offset:128
	global_load_dwordx4 v[18:21], v[0:1], off
	v_cmp_gt_u64_e64 s[0:1], s[8:9], v[2:3]
	v_and_b32_e32 v27, 63, v2
	v_add_u32_e32 v10, 32, v10
	v_cndmask_b32_e64 v26, v11, v12, s[0:1]
	v_and_b32_e32 v26, v26, v2
	v_lshrrev_b32_e32 v26, 6, v26
	v_cndmask_b32_e32 v26, v27, v26, vcc
	v_cvt_f32_ubyte0_e32 v26, v26
	v_mul_f32_e32 v27, v6, v26
	v_mul_f32_e32 v28, v7, v26
	v_mul_f32_e32 v29, v8, v26
	v_mul_f32_e32 v26, v9, v26
	v_mul_f32_e32 v30, 0.15915494, v27
	v_mul_f32_e32 v44, 0.15915494, v26
	v_sin_f32_e32 v27, v30
	v_cos_f32_e32 v26, v30
	v_mul_f32_e32 v43, 0.15915494, v29
	v_mul_f32_e32 v42, 0.15915494, v28
	v_sin_f32_e32 v28, v42
	v_cmp_lt_u32_e64 s[0:1], s12, v10
	s_or_b64 s[4:5], s[0:1], s[4:5]
	v_lshl_add_u64 v[2:3], v[2:3], 0, 16
	s_waitcnt vmcnt(3)
	v_lshlrev_b32_e32 v31, 16, v23
	s_waitcnt vmcnt(2)
	v_lshlrev_b32_e32 v30, 16, v25
	v_and_b32_e32 v33, 0xffff0000, v23
	v_and_b32_e32 v32, 0xffff0000, v25
	v_lshlrev_b32_e32 v35, 16, v22
	v_lshlrev_b32_e32 v34, 16, v24
	v_and_b32_e32 v23, 0xffff0000, v22
	v_and_b32_e32 v22, 0xffff0000, v24
	v_mov_b32_e32 v36, v32
	v_mov_b32_e32 v37, v30
	v_mov_b32_e32 v40, v34
	v_mov_b32_e32 v41, v22
	v_mov_b32_e32 v24, v33
	v_mov_b32_e32 v25, v31
	v_mov_b32_e32 v38, v35
	v_mov_b32_e32 v39, v23
	v_pk_mul_f32 v[36:37], v[36:37], v[36:37]
	v_pk_mul_f32 v[40:41], v[40:41], v[40:41]
	v_pk_fma_f32 v[24:25], v[24:25], v[24:25], v[36:37]
	v_pk_fma_f32 v[36:37], v[38:39], v[38:39], v[40:41]
	s_waitcnt vmcnt(1)
	v_mov_b32_e32 v48, v14
	v_add_f32_e32 v29, v36, v37
	v_add_f32_e32 v25, v25, v29
	v_add_f32_e32 v37, v24, v25
	v_cos_f32_e32 v29, v42
	v_sin_f32_e32 v25, v43
	v_cos_f32_e32 v24, v43
	v_sin_f32_e32 v36, v44
	s_nop 1
	v_add_f32_dpp v41, v37, v37 quad_perm:[1,0,3,2] row_mask:0xf bank_mask:0xf
	v_cos_f32_e32 v37, v44
	s_waitcnt vmcnt(0)
	v_mov_b32_e32 v47, v20
	v_mov_b32_e32 v20, v17
	v_mov_b32_e32 v38, v27
	s_nop 1
	v_add_f32_dpp v45, v41, v41 quad_perm:[2,3,0,1] row_mask:0xf bank_mask:0xf
	v_mov_b32_e32 v39, v26
	v_mov_b32_e32 v40, v29
	v_mov_b32_e32 v41, v28
	v_mov_b32_e32 v42, v25
	s_nop 1
	v_add_f32_dpp v49, v45, v45 row_half_mirror row_mask:0xf bank_mask:0xf
	v_mov_b32_e32 v46, v16
	v_mov_b32_e32 v43, v24
	v_mov_b32_e32 v44, v37
	v_mov_b32_e32 v45, v36
	s_nop 1
	v_add_f32_dpp v14, v49, v49 row_mirror row_mask:0xf bank_mask:0xf
	v_fmamk_f32 v14, v14, 0x3c000000, v13
	v_mul_f32_e32 v16, 0x4b800000, v14
	v_cmp_gt_f32_e64 s[0:1], s3, v14
	v_mov_b32_e32 v49, v18
	v_mov_b32_e32 v18, v15
	v_cndmask_b32_e64 v14, v14, v16, s[0:1]
	v_rsq_f32_e32 v14, v14
	s_nop 0
	v_mul_f32_e32 v15, 0x45800000, v14
	v_cndmask_b32_e64 v14, v14, v15, s[0:1]
	v_pk_mul_f32 v[16:17], v[14:15], v[34:35] op_sel_hi:[0,1]
	v_pk_mul_f32 v[22:23], v[14:15], v[22:23] op_sel_hi:[0,1]
	v_pk_mul_f32 v[30:31], v[14:15], v[30:31] op_sel_hi:[0,1]
	v_pk_mul_f32 v[14:15], v[14:15], v[32:33] op_sel_hi:[0,1]
	v_pk_mul_f32 v[16:17], v[48:49], v[16:17]
	v_pk_mul_f32 v[18:19], v[18:19], v[22:23]
	v_pk_mul_f32 v[22:23], v[46:47], v[30:31]
	v_pk_mul_f32 v[14:15], v[20:21], v[14:15]
	v_pk_mul_f32 v[20:21], v[38:39], v[16:17]
	v_pk_mul_f32 v[16:17], v[26:27], v[16:17]
	v_pk_mul_f32 v[26:27], v[28:29], v[18:19]
	v_pk_mul_f32 v[18:19], v[40:41], v[18:19]
	v_pk_mul_f32 v[28:29], v[42:43], v[22:23]
	v_pk_mul_f32 v[22:23], v[24:25], v[22:23]
	v_pk_mul_f32 v[24:25], v[36:37], v[14:15]
	v_pk_mul_f32 v[14:15], v[44:45], v[14:15]
	v_sub_f32_e32 v20, v21, v20
	v_add_f32_e32 v16, v16, v17
	v_sub_f32_e32 v17, v27, v26
	v_add_f32_e32 v18, v18, v19
	v_sub_f32_e32 v19, v29, v28
	v_add_f32_e32 v21, v22, v23
	v_sub_f32_e32 v22, v25, v24
	v_add_f32_e32 v23, v14, v15
	v_cvt_pk_bf16_f32 v14, v20, v17
	v_cvt_pk_bf16_f32 v15, v19, v22
	v_cvt_pk_bf16_f32 v16, v16, v18
	v_cvt_pk_bf16_f32 v17, v21, v23
	global_store_dwordx2 v[4:5], v[14:15], off
	global_store_dwordx2 v[4:5], v[16:17], off offset:64
	v_lshl_add_u64 v[4:5], v[4:5], 0, s[10:11]
	s_andn2_b64 exec, exec, s[4:5]
	s_cbranch_execnz .LBB0_424
	s_or_b64 exec, exec, s[4:5]

; __device__ __forceinline__ unsigned cvt_pk(float lo, float hi) { unsigned r; asm volatile("v_cvt_pk_bf16_f32 %0, %1, %2" : "=v"(r) : "v"(lo), "v"(hi)); return r; }
; __device__ __forceinline__ float bflo(unsigned w) { return __uint_as_float(w << 16); }
; template <int OUT_F32> __device__ void panel_ln(const bf16_t* Y, const float* xp, const float* xs, const float* g, const float* b, void* dst, int r0) {
;     ...
;     for (int it = 0; it < 32; ++it) {
;         const size_t r = (size_t)r0 + it * 8 + wid;
;         float v[2][8]; float s = 0.f;
; #pragma unroll
;         for (int i = 0; i < 2; ++i) { const u32x4 w = wy[i];
;             v[i][0] = bflo(w.x); v[i][1] = bfhi(w.x); v[i][2] = bflo(w.y); v[i][3] = bfhi(w.y); v[i][4] = bflo(w.z); v[i][5] = bfhi(w.z); v[i][6] = bflo(w.w); v[i][7] = bfhi(w.w);
;             if (!OUT_F32) {
; #pragma unroll
;                 for (int e = 0; e < 4; ++e) { v[i][e] += wx[i][0][e] * ALPHA; v[i][4 + e] += wx[i][1][e] * ALPHA; } }
; #pragma unroll
;             for (int e = 0; e < 8; ++e) s += v[i][e]; }
;         LN_LOAD((it + 1 < 32) ? it + 1 : it);
; #pragma unroll
;         for (int off = 1; off < 64; off <<= 1) s += __shfl_xor(s, off);
;         const float mu = s * (1.f / 1024.f); float q = 0.f;
; #pragma unroll
;         for (int i = 0; i < 2; ++i)
; #pragma unroll
;             for (int e = 0; e < 8; ++e) { v[i][e] -= mu; q += v[i][e] * v[i][e]; }
; #pragma unroll
;         for (int off = 1; off < 64; off <<= 1) q += __shfl_xor(q, off);
;         const float rstd = rsqrtf(q * (1.f / 1024.f) + 1e-5f);
; #pragma unroll
;         for (int i = 0; i < 2; ++i) { const int c = i * 512 + lane * 8; const f32x4 g0 = *(const f32x4*)(g + c), g1 = *(const f32x4*)(g + c + 4), b0 = *(const f32x4*)(b + c), b1 = *(const f32x4*)(b + c + 4);
;             f32x4 o0, o1;
; #pragma unroll
;             for (int e = 0; e < 4; ++e) { o0[e] = v[i][e] * rstd * g0[e] + b0[e]; o1[e] = v[i][4 + e] * rstd * g1[e] + b1[e]; }
;             if (OUT_F32) { __builtin_nontemporal_store(o0, (f32x4*)((float*)dst + r * 1024 + c)); __builtin_nontemporal_store(o1, (f32x4*)((float*)dst + r * 1024 + c + 4)); }
;             else { u32x4 w; w.x = cvt_pk(o0[0], o0[1]); w.y = cvt_pk(o0[2], o0[3]); w.z = cvt_pk(o1[0], o1[1]); w.w = cvt_pk(o1[2], o1[3]); *(u32x4*)((bf16_t*)dst + r * 1024 + c) = w; } }
;     }
.LBB0_612:
	v_lshl_add_u64 v[0:1], v[30:31], 0, s[0:1]
	s_waitcnt vmcnt(0)
	v_lshlrev_b32_e32 v58, 16, v12
	v_and_b32_e32 v59, 0xffff0000, v12
	v_add_co_u32_e32 v64, vcc, 0xc000, v0
	v_add_f32_e32 v0, 0, v58
	v_lshlrev_b32_e32 v12, 16, v13
	v_add_f32_e32 v39, v0, v59
	v_and_b32_e32 v13, 0xffff0000, v13
	v_add_f32_e32 v39, v39, v12
	v_lshlrev_b32_e32 v56, 16, v14
	v_add_f32_e32 v39, v39, v13
	v_and_b32_e32 v57, 0xffff0000, v14
	v_add_f32_e32 v39, v39, v56
	v_lshlrev_b32_e32 v14, 16, v15
	v_add_f32_e32 v39, v39, v57
	v_and_b32_e32 v15, 0xffff0000, v15
	v_add_f32_e32 v39, v39, v14
	v_lshlrev_b32_e32 v62, 16, v8
	v_add_f32_e32 v39, v39, v15
	v_and_b32_e32 v63, 0xffff0000, v8
	v_add_f32_e32 v39, v39, v62
	v_lshlrev_b32_e32 v8, 16, v9
	v_add_f32_e32 v39, v39, v63
	v_and_b32_e32 v9, 0xffff0000, v9
	v_add_f32_e32 v39, v39, v8
	v_lshlrev_b32_e32 v60, 16, v10
	v_add_f32_e32 v39, v39, v9
	v_and_b32_e32 v61, 0xffff0000, v10
	v_add_f32_e32 v39, v39, v60
	v_lshlrev_b32_e32 v10, 16, v11
	v_add_f32_e32 v39, v39, v61
	v_and_b32_e32 v11, 0xffff0000, v11
	v_add_f32_e32 v39, v39, v10
	v_addc_co_u32_e32 v65, vcc, 0, v1, vcc
	v_add_f32_e32 v39, v39, v11
	global_load_dwordx4 v[40:43], v[26:27], off offset:16
	global_load_dwordx4 v[44:47], v[26:27], off
	global_load_dwordx4 v[48:51], v[28:29], off offset:16
	global_load_dwordx4 v[52:55], v[28:29], off
	global_load_dwordx4 v[4:7], v[64:65], off
	global_load_dwordx4 v[0:3], v[64:65], off offset:1024
	s_add_u32 s0, s0, 0xc000
	s_addc_u32 s1, s1, 0
	s_cmp_lg_u32 s0, 0x174000
	s_nop 1
	v_add_f32_dpp v39, v39, v39 quad_perm:[1,0,3,2] row_mask:0xf bank_mask:0xf
	s_nop 1
	v_add_f32_dpp v39, v39, v39 quad_perm:[2,3,0,1] row_mask:0xf bank_mask:0xf
	s_nop 1
	v_add_f32_dpp v39, v39, v39 row_half_mirror row_mask:0xf bank_mask:0xf
	s_nop 1
	v_add_f32_dpp v39, v39, v39 row_mirror row_mask:0xf bank_mask:0xf
	v_mov_b32_e32 v64, v39
	s_nop 1
	v_permlane16_swap_b32_e32 v64, v39
	v_add_f32_e32 v39, v39, v64
	v_mov_b32_e32 v64, v39
	s_nop 1
	v_permlane32_swap_b32_e32 v64, v39
	v_add_f32_e32 v39, v39, v64
	v_mul_f32_e32 v64, 0x3a800000, v39
	v_pk_add_f32 v[58:59], v[58:59], v[64:65] op_sel_hi:[1,0] neg_lo:[0,1] neg_hi:[0,1]
	v_pk_add_f32 v[12:13], v[12:13], v[64:65] op_sel_hi:[1,0] neg_lo:[0,1] neg_hi:[0,1]
	v_pk_add_f32 v[66:67], v[8:9], v[64:65] op_sel_hi:[1,0] neg_lo:[0,1] neg_hi:[0,1]
	v_pk_mul_f32 v[8:9], v[58:59], v[58:59]
	v_pk_add_f32 v[56:57], v[56:57], v[64:65] op_sel_hi:[1,0] neg_lo:[0,1] neg_hi:[0,1]
	v_pk_add_f32 v[14:15], v[14:15], v[64:65] op_sel_hi:[1,0] neg_lo:[0,1] neg_hi:[0,1]
	v_pk_add_f32 v[62:63], v[62:63], v[64:65] op_sel_hi:[1,0] neg_lo:[0,1] neg_hi:[0,1]
	v_pk_add_f32 v[60:61], v[60:61], v[64:65] op_sel_hi:[1,0] neg_lo:[0,1] neg_hi:[0,1]
	v_pk_add_f32 v[64:65], v[10:11], v[64:65] op_sel_hi:[1,0] neg_lo:[0,1] neg_hi:[0,1]
	v_pk_mul_f32 v[10:11], v[12:13], v[12:13]
	v_add_f32_e32 v8, v8, v9
	v_add_f32_e32 v8, v10, v8
	v_pk_mul_f32 v[68:69], v[56:57], v[56:57]
	v_add_f32_e32 v8, v11, v8
	v_add_f32_e32 v8, v68, v8
	v_pk_mul_f32 v[70:71], v[14:15], v[14:15]
	v_add_f32_e32 v8, v69, v8
	v_add_f32_e32 v8, v70, v8
	v_pk_mul_f32 v[72:73], v[62:63], v[62:63]
	v_add_f32_e32 v8, v71, v8
	v_add_f32_e32 v8, v72, v8
	v_pk_mul_f32 v[74:75], v[66:67], v[66:67]
	v_add_f32_e32 v8, v73, v8
	v_add_f32_e32 v8, v74, v8
	v_pk_mul_f32 v[76:77], v[60:61], v[60:61]
	v_add_f32_e32 v8, v75, v8
	v_add_f32_e32 v8, v76, v8
	v_pk_mul_f32 v[78:79], v[64:65], v[64:65]
	v_add_f32_e32 v8, v77, v8
	v_add_f32_e32 v8, v78, v8
	v_add_f32_e32 v8, v79, v8
	s_nop 1
	v_add_f32_dpp v8, v8, v8 quad_perm:[1,0,3,2] row_mask:0xf bank_mask:0xf
	s_nop 1
	v_add_f32_dpp v8, v8, v8 quad_perm:[2,3,0,1] row_mask:0xf bank_mask:0xf
	s_nop 1
	v_add_f32_dpp v8, v8, v8 row_half_mirror row_mask:0xf bank_mask:0xf
	s_nop 1
	v_add_f32_dpp v8, v8, v8 row_mirror row_mask:0xf bank_mask:0xf
	v_mov_b32_e32 v9, v8
	s_nop 1
	v_permlane16_swap_b32_e32 v9, v8
	v_add_f32_e32 v8, v8, v9
	v_mov_b32_e32 v9, v8
	s_nop 1
	v_permlane32_swap_b32_e32 v9, v8
	v_add_f32_e32 v8, v8, v9
	v_fmamk_f32 v8, v8, 0x3a800000, v38
	v_mul_f32_e32 v9, 0x4b800000, v8
	v_cmp_gt_f32_e32 vcc, s4, v8
	s_nop 1
	v_cndmask_b32_e32 v8, v8, v9, vcc
	v_rsq_f32_e32 v8, v8
	s_nop 0
	v_mul_f32_e32 v9, 0x45800000, v8
	v_cndmask_b32_e32 v68, v8, v9, vcc
	v_pk_mul_f32 v[8:9], v[58:59], v[68:69] op_sel_hi:[1,0]
	v_pk_mul_f32 v[10:11], v[12:13], v[68:69] op_sel_hi:[1,0]
	v_pk_mul_f32 v[12:13], v[56:57], v[68:69] op_sel_hi:[1,0]
	v_pk_mul_f32 v[14:15], v[14:15], v[68:69] op_sel_hi:[1,0]
	s_waitcnt vmcnt(2)
	v_pk_fma_f32 v[10:11], v[46:47], v[10:11], v[54:55]
	v_pk_fma_f32 v[8:9], v[44:45], v[8:9], v[52:53]
	v_pk_fma_f32 v[14:15], v[42:43], v[14:15], v[50:51]
	v_pk_fma_f32 v[12:13], v[40:41], v[12:13], v[48:49]
	global_store_dwordx4 v[32:33], v[8:11], off offset:-2048 nt
	global_store_dwordx4 v[32:33], v[12:15], off offset:-2032 nt
	global_load_dwordx4 v[40:43], v[20:21], off
	global_load_dwordx4 v[44:47], v[18:19], off
	global_load_dwordx4 v[48:51], v[18:19], off offset:16
	global_load_dwordx4 v[52:55], v[20:21], off offset:16
	v_pk_mul_f32 v[56:57], v[66:67], v[68:69] op_sel_hi:[1,0]
	v_pk_mul_f32 v[58:59], v[62:63], v[68:69] op_sel_hi:[1,0]
	s_waitcnt vmcnt(6)
	v_mov_b64_e32 v[10:11], v[2:3]
	v_mov_b64_e32 v[14:15], v[6:7]
	v_pk_mul_f32 v[62:63], v[64:65], v[68:69] op_sel_hi:[1,0]
	v_pk_mul_f32 v[60:61], v[60:61], v[68:69] op_sel_hi:[1,0]
	v_mov_b64_e32 v[8:9], v[0:1]
	v_mov_b64_e32 v[12:13], v[4:5]
	s_waitcnt vmcnt(2)
	v_pk_fma_f32 v[40:41], v[44:45], v[58:59], v[40:41]
	v_pk_fma_f32 v[42:43], v[46:47], v[56:57], v[42:43]
	s_waitcnt vmcnt(0)
	v_pk_fma_f32 v[44:45], v[48:49], v[60:61], v[52:53]
	v_pk_fma_f32 v[46:47], v[50:51], v[62:63], v[54:55]
	global_store_dwordx4 v[32:33], v[40:43], off nt
	global_store_dwordx4 v[32:33], v[44:47], off offset:16 nt
	v_lshl_add_u64 v[32:33], v[32:33], 0, s[2:3]
	s_cbranch_scc1 .LBB0_612
; __device__ __forceinline__ unsigned cvt_pk(float lo, float hi) { unsigned r; asm volatile("v_cvt_pk_bf16_f32 %0, %1, %2" : "=v"(r) : "v"(lo), "v"(hi)); return r; }
; __device__ __forceinline__ float bflo(unsigned w) { return __uint_as_float(w << 16); }
; __device__ __forceinline__ float bfhi(unsigned w) { return __uint_as_float(w & 0xffff0000u); }
; template <int OUT_F32> __device__ void panel_ln(const bf16_t* Y, const float* xp, const float* xs, const float* g, const float* b, void* dst, int r0) {
;     ...
;         const size_t r = (size_t)r0 + it * 8 + wid;
;         float v[2][8]; float s = 0.f;
; #pragma unroll
;         for (int i = 0; i < 2; ++i) { const u32x4 w = wy[i];
;             v[i][0] = bflo(w.x); v[i][1] = bfhi(w.x); v[i][2] = bflo(w.y); v[i][3] = bfhi(w.y); v[i][4] = bflo(w.z); v[i][5] = bfhi(w.z); v[i][6] = bflo(w.w); v[i][7] = bfhi(w.w);
;             if (!OUT_F32) {
; #pragma unroll
;                 for (int e = 0; e < 4; ++e) { v[i][e] += wx[i][0][e] * ALPHA; v[i][4 + e] += wx[i][1][e] * ALPHA; } }
; #pragma unroll
;             for (int e = 0; e < 8; ++e) s += v[i][e]; }
;         LN_LOAD((it + 1 < 32) ? it + 1 : it);
; #pragma unroll
;         for (int off = 1; off < 64; off <<= 1) s += __shfl_xor(s, off);
;         const float mu = s * (1.f / 1024.f); float q = 0.f;
; #pragma unroll
;         for (int i = 0; i < 2; ++i)
; #pragma unroll
;             for (int e = 0; e < 8; ++e) { v[i][e] -= mu; q += v[i][e] * v[i][e]; }
; #pragma unroll
;         for (int off = 1; off < 64; off <<= 1) q += __shfl_xor(q, off);
;         const float rstd = rsqrtf(q * (1.f / 1024.f) + 1e-5f);
; #pragma unroll
;         for (int i = 0; i < 2; ++i) { const int c = i * 512 + lane * 8; const f32x4 g0 = *(const f32x4*)(g + c), g1 = *(const f32x4*)(g + c + 4), b0 = *(const f32x4*)(b + c), b1 = *(const f32x4*)(b + c + 4);
;             f32x4 o0, o1;
; #pragma unroll
;             for (int e = 0; e < 4; ++e) { o0[e] = v[i][e] * rstd * g0[e] + b0[e]; o1[e] = v[i][4 + e] * rstd * g1[e] + b1[e]; }
;             if (OUT_F32) { __builtin_nontemporal_store(o0, (f32x4*)((float*)dst + r * 1024 + c)); __builtin_nontemporal_store(o1, (f32x4*)((float*)dst + r * 1024 + c + 4)); }
;             else { u32x4 w; w.x = cvt_pk(o0[0], o0[1]); w.y = cvt_pk(o0[2], o0[3]); w.z = cvt_pk(o1[0], o1[1]); w.w = cvt_pk(o1[2], o1[3]); *(u32x4*)((bf16_t*)dst + r * 1024 + c) = w; } }
	v_lshlrev_b32_e32 v38, 16, v4
	v_and_b32_e32 v39, 0xffff0000, v4
	v_add_f32_e32 v4, 0, v38
	v_add_f32_e32 v4, v4, v39
	v_lshlrev_b32_e32 v40, 16, v5
	v_and_b32_e32 v41, 0xffff0000, v5
	v_add_f32_e32 v4, v4, v40
	v_lshlrev_b32_e32 v30, 16, v6
	v_add_f32_e32 v4, v4, v41
	v_and_b32_e32 v31, 0xffff0000, v6
	v_add_f32_e32 v4, v4, v30
	v_lshlrev_b32_e32 v32, 16, v7
	v_add_f32_e32 v4, v4, v31
	v_and_b32_e32 v33, 0xffff0000, v7
	v_add_f32_e32 v4, v4, v32
	v_add_f32_e32 v4, v4, v33
	v_lshlrev_b32_e32 v46, 16, v0
	v_and_b32_e32 v47, 0xffff0000, v0
	v_add_f32_e32 v0, v4, v46
	v_add_f32_e32 v0, v0, v47
	v_lshlrev_b32_e32 v48, 16, v1
	v_and_b32_e32 v49, 0xffff0000, v1
	v_add_f32_e32 v0, v0, v48
	v_lshlrev_b32_e32 v42, 16, v2
	v_add_f32_e32 v0, v0, v49
	v_and_b32_e32 v43, 0xffff0000, v2
	v_add_f32_e32 v0, v0, v42
	v_lshlrev_b32_e32 v44, 16, v3
	v_add_f32_e32 v0, v0, v43
	v_and_b32_e32 v45, 0xffff0000, v3
	v_add_f32_e32 v0, v0, v44
	v_add_f32_e32 v0, v0, v45
	s_mov_b32 s2, 0x800000
	v_lshl_add_u64 v[24:25], s[76:77], 0, v[24:25]
	s_mov_b64 s[0:1], 0xf8000
	v_lshlrev_b32_e32 v22, 2, v22
	s_nop 1
	v_add_f32_dpp v0, v0, v0 quad_perm:[1,0,3,2] row_mask:0xf bank_mask:0xf
	v_lshl_add_u64 v[24:25], v[24:25], 0, s[0:1]
	s_nop 1
	v_add_f32_dpp v0, v0, v0 quad_perm:[2,3,0,1] row_mask:0xf bank_mask:0xf
	s_nop 1
	v_add_f32_dpp v0, v0, v0 row_half_mirror row_mask:0xf bank_mask:0xf
	s_nop 1
	v_add_f32_dpp v0, v0, v0 row_mirror row_mask:0xf bank_mask:0xf
	v_mov_b32_e32 v1, v0
	v_mov_b32_e32 v50, v0
	s_nop 1
	v_permlane16_swap_b32_e32 v1, v50
	v_add_f32_e32 v50, v50, v1
	global_load_dwordx4 v[0:3], v[26:27], off offset:16
	global_load_dwordx4 v[4:7], v[26:27], off
	global_load_dwordx4 v[8:11], v[28:29], off offset:16
	global_load_dwordx4 v[12:15], v[28:29], off
	v_mov_b32_e32 v51, v50
	v_mov_b32_e32 v26, v50
	s_nop 1
	v_permlane32_swap_b32_e32 v51, v26
	v_add_f32_e32 v26, v26, v51
	v_mul_f32_e32 v26, 0x3a800000, v26
	v_pk_add_f32 v[28:29], v[38:39], v[26:27] op_sel_hi:[1,0] neg_lo:[0,1] neg_hi:[0,1]
	v_pk_add_f32 v[38:39], v[40:41], v[26:27] op_sel_hi:[1,0] neg_lo:[0,1] neg_hi:[0,1]
	v_pk_mul_f32 v[40:41], v[28:29], v[28:29]
	v_pk_mul_f32 v[50:51], v[38:39], v[38:39]
	v_add_f32_e32 v40, v40, v41
	v_pk_add_f32 v[30:31], v[30:31], v[26:27] op_sel_hi:[1,0] neg_lo:[0,1] neg_hi:[0,1]
	v_add_f32_e32 v40, v50, v40
	v_pk_mul_f32 v[52:53], v[30:31], v[30:31]
	v_add_f32_e32 v40, v51, v40
	v_pk_add_f32 v[32:33], v[32:33], v[26:27] op_sel_hi:[1,0] neg_lo:[0,1] neg_hi:[0,1]
	v_add_f32_e32 v40, v52, v40
	v_pk_mul_f32 v[54:55], v[32:33], v[32:33]
	v_add_f32_e32 v40, v53, v40
	v_pk_add_f32 v[46:47], v[46:47], v[26:27] op_sel_hi:[1,0] neg_lo:[0,1] neg_hi:[0,1]
	v_add_f32_e32 v40, v54, v40
	v_pk_mul_f32 v[56:57], v[46:47], v[46:47]
	v_add_f32_e32 v40, v55, v40
	v_pk_add_f32 v[48:49], v[48:49], v[26:27] op_sel_hi:[1,0] neg_lo:[0,1] neg_hi:[0,1]
	v_add_f32_e32 v40, v56, v40
	v_pk_mul_f32 v[58:59], v[48:49], v[48:49]
	v_add_f32_e32 v40, v57, v40
	v_pk_add_f32 v[42:43], v[42:43], v[26:27] op_sel_hi:[1,0] neg_lo:[0,1] neg_hi:[0,1]
	v_add_f32_e32 v40, v58, v40
	v_pk_mul_f32 v[60:61], v[42:43], v[42:43]
	v_add_f32_e32 v40, v59, v40
	v_pk_add_f32 v[26:27], v[44:45], v[26:27] op_sel_hi:[1,0] neg_lo:[0,1] neg_hi:[0,1]
	v_add_f32_e32 v40, v60, v40
	v_pk_mul_f32 v[44:45], v[26:27], v[26:27]
	v_add_f32_e32 v40, v61, v40
	v_add_f32_e32 v40, v44, v40
	v_add_f32_e32 v40, v45, v40
	s_nop 1
	v_add_f32_dpp v17, v40, v40 quad_perm:[1,0,3,2] row_mask:0xf bank_mask:0xf
	s_nop 1
	v_add_f32_dpp v17, v17, v17 quad_perm:[2,3,0,1] row_mask:0xf bank_mask:0xf
	v_mov_b32_e32 v34, 0x3727c5ac
	s_nop 1
	v_add_f32_dpp v17, v17, v17 row_half_mirror row_mask:0xf bank_mask:0xf
	s_nop 1
	v_add_f32_dpp v17, v17, v17 row_mirror row_mask:0xf bank_mask:0xf
	v_mov_b32_e32 v23, v17
	s_nop 1
	v_permlane16_swap_b32_e32 v23, v17
	v_add_f32_e32 v17, v17, v23
	v_mov_b32_e32 v23, v17
	s_nop 1
	v_permlane32_swap_b32_e32 v23, v17
	v_add_f32_e32 v17, v17, v23
	v_fmac_f32_e32 v34, 0x3a800000, v17
	v_mul_f32_e32 v17, 0x4b800000, v34
	v_cmp_gt_f32_e32 vcc, s2, v34
	v_mov_b32_e32 v23, 0
	s_nop 0
	v_cndmask_b32_e32 v17, v34, v17, vcc
	v_rsq_f32_e32 v17, v17
	v_lshl_add_u64 v[34:35], v[24:25], 0, v[22:23]
	v_mul_f32_e32 v22, 0x45800000, v17
	v_cndmask_b32_e32 v36, v17, v22, vcc
	v_pk_mul_f32 v[28:29], v[28:29], v[36:37] op_sel_hi:[1,0]
	v_pk_mul_f32 v[38:39], v[38:39], v[36:37] op_sel_hi:[1,0]
	v_pk_mul_f32 v[30:31], v[30:31], v[36:37] op_sel_hi:[1,0]
	v_pk_mul_f32 v[32:33], v[32:33], v[36:37] op_sel_hi:[1,0]
	s_waitcnt vmcnt(0)
	v_pk_fma_f32 v[6:7], v[6:7], v[38:39], v[14:15]
	v_pk_fma_f32 v[4:5], v[4:5], v[28:29], v[12:13]
	v_pk_fma_f32 v[2:3], v[2:3], v[32:33], v[10:11]
	v_pk_fma_f32 v[0:1], v[0:1], v[30:31], v[8:9]
	global_store_dwordx4 v[34:35], v[4:7], off nt
	global_store_dwordx4 v[34:35], v[0:3], off offset:16 nt
	global_load_dwordx4 v[0:3], v[20:21], off
	s_nop 0
	global_load_dwordx4 v[4:7], v[18:19], off
	global_load_dwordx4 v[8:11], v[18:19], off offset:16
	global_load_dwordx4 v[12:15], v[20:21], off offset:16
	v_lshlrev_b32_e32 v22, 2, v16
	v_pk_mul_f32 v[18:19], v[48:49], v[36:37] op_sel_hi:[1,0]
	v_pk_mul_f32 v[20:21], v[46:47], v[36:37] op_sel_hi:[1,0]
	v_lshl_add_u64 v[16:17], v[24:25], 0, v[22:23]
	v_pk_mul_f32 v[22:23], v[26:27], v[36:37] op_sel_hi:[1,0]
	v_pk_mul_f32 v[24:25], v[42:43], v[36:37] op_sel_hi:[1,0]
	s_waitcnt vmcnt(2)
	v_pk_fma_f32 v[0:1], v[4:5], v[20:21], v[0:1]
	v_pk_fma_f32 v[2:3], v[6:7], v[18:19], v[2:3]
	s_waitcnt vmcnt(0)
	v_pk_fma_f32 v[4:5], v[8:9], v[24:25], v[12:13]
	v_pk_fma_f32 v[6:7], v[10:11], v[22:23], v[14:15]
	global_store_dwordx4 v[16:17], v[0:3], off nt
	global_store_dwordx4 v[16:17], v[4:7], off offset:16 nt
